# GEMM prologues: second tile-DMA group issued before the first wait (7 phases)
# speedup vs baseline: 1.0116x; 1.0030x over previous
; #define PG8_STAGE(bufoff, gbase, voff) do { _Pragma("unroll") for (int _i = 0; _i < 2; ++_i) \
;         __builtin_amdgcn_global_load_lds((const unsigned*)((const char*)(gbase) + (voff)[_i]), (LAS unsigned*)(lds + (bufoff) + ldsw + _i * 8192), 16, 0, 0); } while (0)
; #define PG8_WAIT_V(n) asm volatile("s_waitcnt vmcnt(" #n ")" ::: "memory")
; #define PG8_BAR __builtin_amdgcn_s_barrier()
; template <class Epi, class Sched, bool DEFER>
; __device__ __forceinline__ void gemm_fast_core(LAS unsigned char* lds, const GemmP g, const Sched& S, const Epi& E, f32x4 (&acc)[2][2][4][2], Unit& cur) {
;     ...
;     const char* cA = (const char*)g.aptr(cur); const char* cB = (const char*)g.bptr(cur);
;     PG8_STAGE(PG8_SB(0, 0), cB, voffB); PG8_STAGE(PG8_SB(0, 1), cB + hstepB, voffB); PG8_STAGE(PG8_SA(0, 0), cA, voffA); PG8_STAGE(PG8_SA(0, 1), cA + hstepA, voffA);
;     if (wr == 1) PG8_BAR;
;     PG8_WAIT_V(2); PG8_BAR;
;     PG8_STAGE(PG8_SB(1, 0), cB + kstep, voffB); PG8_STAGE(PG8_SA(1, 0), cA + kstep, voffA); PG8_STAGE(PG8_SB(1, 1), cB + hstepB + kstep, voffB);
;     PG8_WAIT_V(6); PG8_BAR;
.LBB0_227:
	s_lshl_b32 s16, s16, 5
	s_and_b32 s20, s16, 0x60
	s_mov_b64 s[16:17], 0x80
	s_add_i32 m0, s48, 0x18000
	v_lshl_add_u64 v[6:7], v[6:7], 0, s[16:17]
	s_lshl_b32 s3, s19, 13
	s_lshl_b32 s24, s20, 7
	global_load_lds_dwordx4 v[6:7], off
	v_lshl_add_u64 v[4:5], v[4:5], 0, s[16:17]
	s_add_i32 m0, s48, 0x1a000
	s_add_i32 s74, s48, 0x8000
	s_add_i32 s75, s48, 0xa000
	global_load_lds_dwordx4 v[4:5], off
	v_lshl_add_u64 v[0:1], v[0:1], 0, s[16:17]
	s_mov_b32 m0, s74
	s_add_u32 s22, s38, 0x80080
	global_load_lds_dwordx4 v[0:1], off
	v_lshl_add_u64 v[0:1], v[2:3], 0, s[16:17]
	s_mov_b32 m0, s75
	s_addc_u32 s23, s39, 0
	global_load_lds_dwordx4 v[0:1], off
	s_add_i32 m0, s48, 0x1c000
	v_lshl_add_u64 v[0:1], s[22:23], 0, v[128:129]
	global_load_lds_dwordx4 v[0:1], off
	v_lshl_add_u64 v[0:1], s[22:23], 0, v[130:131]
	s_add_i32 m0, s48, 0x1e000
	s_cmpk_lt_u32 s18, 0x100
	global_load_lds_dwordx4 v[0:1], off
	s_waitcnt vmcnt(8)
	s_barrier
	v_bfe_u32 v1, v8, 4, 2
	v_and_b32_e32 v0, 15, v8
	v_lshlrev_b32_e32 v2, 4, v1
	v_lshl_or_b32 v140, s19, 6, v0
	v_lshl_or_b32 v0, v0, 6, v2
	v_lshlrev_b32_e32 v2, 2, v8
	v_and_b32_e32 v2, 32, v2
	v_bitop3_b32 v3, v0, s3, v2 bitop3:0xde
	v_bitop3_b32 v141, v0, s24, v2 bitop3:0xde
	v_lshlrev_b32_e32 v0, 15, v9
	v_and_b32_e32 v0, 0xffff0000, v0
	v_lshl_or_b32 v142, v1, 2, s20
	v_lshl_add_u32 v0, v10, 12, v0
	v_and_b32_e32 v1, 1, v9
	v_lshl_or_b32 v0, v1, 6, v0
	v_lshl_add_u32 v132, v11, 1, v0
	v_lshlrev_b32_e32 v0, 15, v12
	v_and_b32_e32 v0, 0xffff0000, v0
	s_waitcnt vmcnt(6)
	v_lshl_add_u32 v0, v13, 12, v0
	v_and_b32_e32 v1, 1, v12
	s_cselect_b64 s[18:19], -1, 0
	v_lshl_or_b32 v0, v1, 6, v0
	s_add_i32 s76, 0, 0x10000
	s_add_i32 s77, 0, 0x14000
	v_mov_b32_e32 v133, v129
	v_lshl_add_u32 v134, v14, 1, v0
	v_mov_b32_e32 v135, v129
	v_add_u32_e32 v143, s76, v141
	v_add_u32_e32 v144, s77, v141
	v_add_u32_e32 v145, 0, v3
	s_movk_i32 s78, 0xe800
	s_movk_i32 s79, 0x800
	s_mov_b32 s20, 0x3db504f3
	s_barrier
	s_branch .LBB0_230

; #define PG8_STAGE(bufoff, gbase, voff) do { _Pragma("unroll") for (int _i = 0; _i < 2; ++_i) \
;         __builtin_amdgcn_global_load_lds((const unsigned*)((const char*)(gbase) + (voff)[_i]), (LAS unsigned*)(lds + (bufoff) + ldsw + _i * 8192), 16, 0, 0); } while (0)
; #define PG8_WAIT_V(n) asm volatile("s_waitcnt vmcnt(" #n ")" ::: "memory")
; #define PG8_BAR __builtin_amdgcn_s_barrier()
; template <class Epi, class Sched, bool DEFER>
; __device__ __forceinline__ void gemm_fast_core(LAS unsigned char* lds, const GemmP g, const Sched& S, const Epi& E, f32x4 (&acc)[2][2][4][2], Unit& cur) {
;     ...
;     PG8_STAGE(PG8_SB(0, 0), cB, voffB); PG8_STAGE(PG8_SB(0, 1), cB + hstepB, voffB); PG8_STAGE(PG8_SA(0, 0), cA, voffA); PG8_STAGE(PG8_SA(0, 1), cA + hstepA, voffA);
;     if (wr == 1) PG8_BAR;
;     PG8_WAIT_V(2); PG8_BAR;
;     PG8_STAGE(PG8_SB(1, 0), cB + kstep, voffB); PG8_STAGE(PG8_SA(1, 0), cA + kstep, voffA); PG8_STAGE(PG8_SB(1, 1), cB + hstepB + kstep, voffB);
;     PG8_WAIT_V(6); PG8_BAR;
.LBB0_1029:
	v_bfe_u32 v10, v8, 4, 2
	v_and_b32_e32 v9, 15, v8
	v_lshlrev_b32_e32 v11, 4, v10
	v_lshlrev_b32_e32 v8, 2, v8
	s_sext_i32_i8 s27, s4
	v_lshl_or_b32 v138, s10, 6, v9
	v_lshl_or_b32 v9, v9, 6, v11
	s_lshl_b32 s4, s10, 13
	v_and_b32_e32 v8, 32, v8
	v_bitop3_b32 v11, v9, s4, v8 bitop3:0xde
	s_lshl_b32 s4, s11, 5
	s_and_b32 s4, s4, 0x60
	s_lshl_b32 s10, s4, 7
	v_bitop3_b32 v139, v9, s10, v8 bitop3:0xde
	s_mov_b64 s[10:11], 0x80
	s_add_i32 m0, s29, 0x18000
	v_lshl_add_u64 v[6:7], v[6:7], 0, s[10:11]
	global_load_lds_dwordx4 v[6:7], off
	v_lshl_add_u64 v[2:3], v[2:3], 0, s[10:11]
	s_add_i32 m0, s29, 0x1a000
	s_add_i32 s49, s29, 0x8000
	s_add_i32 s54, s29, 0xa000
	global_load_lds_dwordx4 v[2:3], off
	v_lshl_add_u64 v[0:1], v[0:1], 0, s[10:11]
	s_mov_b32 m0, s49
	s_add_u32 s16, s42, 0x40080
	global_load_lds_dwordx4 v[0:1], off
	v_lshl_add_u64 v[0:1], v[4:5], 0, s[10:11]
	s_mov_b32 m0, s54
	s_addc_u32 s17, s43, 0
	global_load_lds_dwordx4 v[0:1], off
	s_add_i32 m0, s29, 0x1c000
	v_lshl_add_u64 v[0:1], s[16:17], 0, v[130:131]
	global_load_lds_dwordx4 v[0:1], off
	v_lshl_add_u64 v[0:1], s[16:17], 0, v[134:135]
	s_add_i32 m0, s29, 0x1e000
	s_cmpk_lt_u32 s5, 0x100
	global_load_lds_dwordx4 v[0:1], off
	s_waitcnt vmcnt(8)
	s_barrier
	s_waitcnt vmcnt(6)
	v_lshlrev_b32_e32 v0, 12, v138
	s_cselect_b64 s[16:17], -1, 0
	v_and_b32_e32 v0, 0xcf000, v0
	s_add_i32 s68, 0, 0x10000
	s_add_i32 s69, 0, 0x14000
	v_lshl_or_b32 v140, v10, 2, s4
	s_mov_b32 s84, s88
	s_add_i32 s55, s88, s86
	v_add_u32_e32 v141, s68, v139
	v_add_u32_e32 v142, s69, v139
	v_add_u32_e32 v143, 0, v11
	s_mov_b64 s[18:19], 0x100
	s_mov_b64 s[20:21], 0x180
	v_lshlrev_b32_e32 v136, 1, v0
	s_mov_b64 s[22:23], 0x20000
	s_mov_b32 s70, 0x20000
	s_mov_b32 s71, 0x40000
	s_mov_b64 s[24:25], 0x60000
	s_mov_b32 s72, 0x60000
	s_barrier
	s_branch .LBB0_1032

; #define PG8_STAGE(bufoff, gbase, voff) do { _Pragma("unroll") for (int _i = 0; _i < 2; ++_i) \
;         __builtin_amdgcn_global_load_lds((const unsigned*)((const char*)(gbase) + (voff)[_i]), (LAS unsigned*)(lds + (bufoff) + ldsw + _i * 8192), 16, 0, 0); } while (0)
; #define PG8_WAIT_V(n) asm volatile("s_waitcnt vmcnt(" #n ")" ::: "memory")
; #define PG8_BAR __builtin_amdgcn_s_barrier()
; template <class Epi, class Sched, bool DEFER>
; __device__ __forceinline__ void gemm_fast_core(LAS unsigned char* lds, const GemmP g, const Sched& S, const Epi& E, f32x4 (&acc)[2][2][4][2], Unit& cur) {
;     ...
;     PG8_STAGE(PG8_SB(0, 0), cB, voffB); PG8_STAGE(PG8_SB(0, 1), cB + hstepB, voffB); PG8_STAGE(PG8_SA(0, 0), cA, voffA); PG8_STAGE(PG8_SA(0, 1), cA + hstepA, voffA);
;     if (wr == 1) PG8_BAR;
;     PG8_WAIT_V(2); PG8_BAR;
;     PG8_STAGE(PG8_SB(1, 0), cB + kstep, voffB); PG8_STAGE(PG8_SA(1, 0), cA + kstep, voffA); PG8_STAGE(PG8_SB(1, 1), cB + hstepB + kstep, voffB);
;     PG8_WAIT_V(6); PG8_BAR;
.LBB0_1207:
	s_lshl_b32 s5, s5, 5
	s_mov_b64 s[10:11], 0x80
	s_and_b32 s5, s5, 0x60
	s_add_i32 m0, s29, 0x18000
	v_lshl_add_u64 v[6:7], v[6:7], 0, s[10:11]
	s_lshl_b32 s13, s4, 13
	s_lshl_b32 s14, s5, 7
	global_load_lds_dwordx4 v[6:7], off
	v_lshl_add_u64 v[4:5], v[4:5], 0, s[10:11]
	s_add_i32 m0, s29, 0x1a000
	s_add_i32 s34, s29, 0x8000
	s_add_i32 s35, s29, 0xa000
	global_load_lds_dwordx4 v[4:5], off
	v_lshl_add_u64 v[0:1], v[0:1], 0, s[10:11]
	s_mov_b32 m0, s34
	s_add_u32 s16, s24, 0x100080
	global_load_lds_dwordx4 v[0:1], off
	v_lshl_add_u64 v[0:1], v[2:3], 0, s[10:11]
	s_mov_b32 m0, s35
	s_addc_u32 s17, s25, 0
	global_load_lds_dwordx4 v[0:1], off
	s_add_i32 m0, s29, 0x1c000
	v_lshl_add_u64 v[0:1], s[16:17], 0, v[128:129]
	global_load_lds_dwordx4 v[0:1], off
	v_lshl_add_u64 v[0:1], s[16:17], 0, v[130:131]
	s_add_i32 m0, s29, 0x1e000
	s_cmpk_lt_u32 s12, 0x100
	global_load_lds_dwordx4 v[0:1], off
	s_waitcnt vmcnt(8)
	s_barrier
	v_bfe_u32 v1, v8, 4, 2
	v_and_b32_e32 v0, 15, v8
	v_lshlrev_b32_e32 v2, 4, v1
	v_lshl_or_b32 v140, s4, 6, v0
	v_lshl_or_b32 v0, v0, 6, v2
	v_lshlrev_b32_e32 v2, 2, v8
	v_and_b32_e32 v2, 32, v2
	v_bitop3_b32 v3, v0, s13, v2 bitop3:0xde
	v_bitop3_b32 v141, v0, s14, v2 bitop3:0xde
	v_lshl_or_b32 v0, v1, 2, s5
	v_lshlrev_b32_e32 v1, 16, v9
	v_and_b32_e32 v1, 0xfffe0000, v1
	v_lshl_add_u32 v1, v10, 13, v1
	v_and_b32_e32 v2, 1, v9
	v_lshl_or_b32 v1, v2, 6, v1
	v_lshl_add_u32 v134, v11, 1, v1
	v_lshlrev_b32_e32 v1, 16, v12
	v_and_b32_e32 v1, 0xfffe0000, v1
	s_waitcnt vmcnt(6)
	v_lshl_add_u32 v1, v13, 13, v1
	v_and_b32_e32 v2, 1, v12
	s_cselect_b64 s[12:13], -1, 0
	v_lshl_or_b32 v1, v2, 6, v1
	s_add_i32 s36, 0, 0x10000
	s_add_i32 s37, 0, 0x14000
	v_mov_b32_e32 v135, v133
	v_lshl_add_u32 v136, v14, 1, v1
	v_mov_b32_e32 v137, v133
	v_add_u32_e32 v142, s36, v141
	v_add_u32_e32 v143, s37, v141
	v_add_u32_e32 v144, 0, v3
	v_lshlrev_b32_e32 v132, 1, v0
	s_mov_b32 s14, 0x3cb504f3
	s_mov_b32 s38, 0
	s_barrier
	s_branch .LBB0_1210

; #define PG8_STAGE(bufoff, gbase, voff) do { _Pragma("unroll") for (int _i = 0; _i < 2; ++_i) \
;         __builtin_amdgcn_global_load_lds((const unsigned*)((const char*)(gbase) + (voff)[_i]), (LAS unsigned*)(lds + (bufoff) + ldsw + _i * 8192), 16, 0, 0); } while (0)
; #define PG8_WAIT_V(n) asm volatile("s_waitcnt vmcnt(" #n ")" ::: "memory")
; #define PG8_BAR __builtin_amdgcn_s_barrier()
;     __device__ __forceinline__ bool decode(int L, Unit& u) const {
;     ...
;         int wgid = L; { const int q = nwg / NXCD, r = nwg % NXCD, xcd = wgid % NXCD, off = wgid / NXCD; wgid = (xcd < r ? xcd * (q + 1) : r * (q + 1) + (xcd - r) * q) + off; }
;         const int nig = WGM * nN, gid = wgid / nig, fm = gid * WGM, gsz = (nMt - fm) < WGM ? (nMt - fm) : WGM;
;         const int pmt = fm + ((wgid % nig) % gsz); u.pn = (wgid % nig) / gsz; u.bz = pmt / nMb; u.pm = pmt % nMb; return true;
; template <class Epi, class Sched, bool DEFER>
; __device__ __forceinline__ void gemm_fast_core(LAS unsigned char* lds, const GemmP g, const Sched& S, const Epi& E, f32x4 (&acc)[2][2][4][2], Unit& cur) {
;     ...
;     PG8_STAGE(PG8_SB(0, 0), cB, voffB); PG8_STAGE(PG8_SB(0, 1), cB + hstepB, voffB); PG8_STAGE(PG8_SA(0, 0), cA, voffA); PG8_STAGE(PG8_SA(0, 1), cA + hstepA, voffA);
;     if (wr == 1) PG8_BAR;
;     PG8_WAIT_V(2); PG8_BAR;
;     PG8_STAGE(PG8_SB(1, 0), cB + kstep, voffB); PG8_STAGE(PG8_SA(1, 0), cA + kstep, voffA); PG8_STAGE(PG8_SB(1, 1), cB + hstepB + kstep, voffB);
;     PG8_WAIT_V(6); PG8_BAR;
.LBB0_1406:
	v_bfe_u32 v16, v12, 4, 2
	v_and_b32_e32 v15, 15, v12
	v_lshlrev_b32_e32 v17, 4, v16
	v_lshlrev_b32_e32 v12, 2, v12
	v_lshl_or_b32 v148, s6, 6, v15
	v_lshl_or_b32 v15, v15, 6, v17
	s_lshl_b32 s5, s6, 13
	v_and_b32_e32 v12, 32, v12
	v_bitop3_b32 v17, v15, s5, v12 bitop3:0xde
	s_lshl_b32 s5, s7, 5
	s_and_b32 s5, s5, 0x60
	s_lshl_b32 s6, s5, 7
	v_bitop3_b32 v149, v15, s6, v12 bitop3:0xde
	s_mov_b64 s[6:7], 0x80
	s_add_i32 m0, s39, 0x18000
	v_lshl_add_u64 v[6:7], v[6:7], 0, s[6:7]
	global_load_lds_dwordx4 v[6:7], off
	v_lshl_add_u64 v[4:5], v[4:5], 0, s[6:7]
	s_add_i32 m0, s39, 0x1a000
	s_add_i32 s43, s39, 0x8000
	s_add_i32 s44, s39, 0xa000
	global_load_lds_dwordx4 v[4:5], off
	v_lshl_add_u64 v[0:1], v[0:1], 0, s[6:7]
	s_mov_b32 m0, s43
	s_add_u32 s10, s34, 0x40080
	global_load_lds_dwordx4 v[0:1], off
	v_lshl_add_u64 v[0:1], v[2:3], 0, s[6:7]
	s_mov_b32 m0, s44
	s_addc_u32 s11, s35, 0
	global_load_lds_dwordx4 v[0:1], off
	s_add_i32 m0, s39, 0x1c000
	v_lshl_add_u64 v[0:1], s[10:11], 0, v[128:129]
	global_load_lds_dwordx4 v[0:1], off
	v_lshl_add_u64 v[0:1], s[10:11], 0, v[130:131]
	s_add_i32 m0, s39, 0x1e000
	s_cmpk_lt_u32 s8, 0x100
	global_load_lds_dwordx4 v[0:1], off
	s_waitcnt vmcnt(8)
	s_barrier
	s_cselect_b64 s[8:9], -1, 0
	s_ashr_i32 s10, s88, 31
	s_lshr_b32 s10, s10, 29
	s_add_i32 s10, s88, s10
	s_ashr_i32 s11, s10, 3
	s_and_b32 s10, s10, -8
	s_sub_i32 s10, s88, s10
	s_lshl_b32 s12, s10, 5
	s_cmp_lt_i32 s10, 0
	s_mul_i32 s10, s10, 33
	s_cselect_b32 s10, s10, s12
	s_add_i32 s10, s10, s11
	s_ashr_i32 s11, s10, 31
	s_lshr_b32 s11, s11, 26
	s_add_i32 s11, s10, s11
	s_ashr_i32 s11, s11, 6
	s_lshl_b32 s12, s11, 3
	s_sub_i32 s13, 32, s12
	s_min_i32 s13, s13, 8
	s_abs_i32 s14, s13
	v_cvt_f32_u32_e32 v0, s14
	s_sub_i32 s15, 0, s14
	s_lshl_b32 s11, s11, 6
	s_sub_i32 s11, s10, s11
	v_rcp_iflag_f32_e32 v0, v0
	s_abs_i32 s10, s11
	v_lshl_or_b32 v150, v16, 2, s5
	s_xor_b32 s5, s11, s13
	v_mul_f32_e32 v0, 0x4f7ffffe, v0
	v_cvt_u32_f32_e32 v0, v0
	s_ashr_i32 s5, s5, 31
	v_and_b32_e32 v1, 1, v8
	s_waitcnt vmcnt(6)
	v_readfirstlane_b32 s16, v0
	s_mul_i32 s15, s15, s16
	s_mul_hi_u32 s15, s16, s15
	s_add_i32 s16, s16, s15
	s_mul_hi_u32 s15, s10, s16
	s_mul_i32 s16, s15, s14
	s_sub_i32 s10, s10, s16
	s_add_i32 s16, s15, 1
	s_sub_i32 s17, s10, s14
	s_cmp_ge_u32 s10, s14
	s_cselect_b32 s15, s16, s15
	s_cselect_b32 s10, s17, s10
	s_add_i32 s16, s15, 1
	s_cmp_ge_u32 s10, s14
	s_cselect_b32 s10, s16, s15
	s_xor_b32 s10, s10, s5
	s_sub_i32 s10, s10, s5
	v_lshlrev_b32_e32 v0, 14, v8
	s_mul_i32 s5, s10, s13
	v_and_b32_e32 v0, 0xffff8000, v0
	s_sub_i32 s5, s11, s5
	v_lshl_add_u32 v0, v9, 11, v0
	s_add_i32 s5, s12, s5
	v_lshl_or_b32 v0, v1, 6, v0
	s_ashr_i32 s11, s5, 31
	v_lshl_add_u32 v132, v10, 1, v0
	v_lshlrev_b32_e32 v0, 14, v11
	s_lshr_b32 s11, s11, 27
	v_and_b32_e32 v0, 0xffff8000, v0
	s_add_i32 s11, s5, s11
	v_lshl_add_u32 v0, v13, 11, v0
	v_and_b32_e32 v1, 1, v11
	s_andn2_b32 s11, s11, 31
	v_lshl_or_b32 v0, v1, 6, v0
	s_add_i32 s45, 0, 0x10000
	s_add_i32 s46, 0, 0x14000
	s_sub_i32 s12, s5, s11
	v_mov_b32_e32 v133, v129
	v_lshl_add_u32 v134, v14, 1, v0
	v_mov_b32_e32 v135, v129
	s_mov_b64 s[20:21], -1
	v_add_u32_e32 v151, s45, v149
	v_add_u32_e32 v152, s46, v149
	v_add_u32_e32 v153, 0, v17
	s_mov_b64 s[14:15], 0x48000
	s_mov_b64 s[16:17], 0x50000
	s_mov_b64 s[18:19], 0x58000
	s_barrier
	s_branch .LBB0_1409

; #define PG8_STAGE(bufoff, gbase, voff) do { _Pragma("unroll") for (int _i = 0; _i < 2; ++_i) \
;         __builtin_amdgcn_global_load_lds((const unsigned*)((const char*)(gbase) + (voff)[_i]), (LAS unsigned*)(lds + (bufoff) + ldsw + _i * 8192), 16, 0, 0); } while (0)
; #define PG8_WAIT_V(n) asm volatile("s_waitcnt vmcnt(" #n ")" ::: "memory")
; #define PG8_BAR __builtin_amdgcn_s_barrier()
; template <class Epi, class Sched, bool DEFER>
; __device__ __forceinline__ void gemm_fast_core(LAS unsigned char* lds, const GemmP g, const Sched& S, const Epi& E, f32x4 (&acc)[2][2][4][2], Unit& cur) {
;     ...
;     PG8_STAGE(PG8_SB(0, 0), cB, voffB); PG8_STAGE(PG8_SB(0, 1), cB + hstepB, voffB); PG8_STAGE(PG8_SA(0, 0), cA, voffA); PG8_STAGE(PG8_SA(0, 1), cA + hstepA, voffA);
;     if (wr == 1) PG8_BAR;
;     PG8_WAIT_V(2); PG8_BAR;
;     PG8_STAGE(PG8_SB(1, 0), cB + kstep, voffB); PG8_STAGE(PG8_SA(1, 0), cA + kstep, voffA); PG8_STAGE(PG8_SB(1, 1), cB + hstepB + kstep, voffB);
;     PG8_WAIT_V(6); PG8_BAR;
.LBB0_1605:
	s_lshl_b32 s6, s6, 12
	s_lshl_b32 s1, s7, 13
	s_and_b32 s11, s6, 0x3000
	s_mov_b64 s[6:7], 0x80
	s_add_i32 m0, s25, 0x18000
	v_lshl_add_u64 v[10:11], v[10:11], 0, s[6:7]
	global_load_lds_dwordx4 v[10:11], off
	v_lshl_add_u64 v[8:9], v[8:9], 0, s[6:7]
	s_add_i32 m0, s25, 0x1a000
	s_add_i32 s30, s25, 0x8000
	s_add_i32 s31, s25, 0xa000
	global_load_lds_dwordx4 v[8:9], off
	v_lshl_add_u64 v[4:5], v[4:5], 0, s[6:7]
	s_mov_b32 m0, s30
	s_add_u32 s8, s20, 0x80080
	global_load_lds_dwordx4 v[4:5], off
	v_lshl_add_u64 v[4:5], v[6:7], 0, s[6:7]
	s_mov_b32 m0, s31
	s_addc_u32 s9, s21, 0
	global_load_lds_dwordx4 v[4:5], off
	s_add_i32 m0, s25, 0x1c000
	v_lshl_add_u64 v[4:5], s[8:9], 0, v[0:1]
	global_load_lds_dwordx4 v[4:5], off
	v_lshl_add_u64 v[4:5], s[8:9], 0, v[2:3]
	s_add_i32 m0, s25, 0x1e000
	v_lshlrev_b32_e32 v7, 2, v12
	global_load_lds_dwordx4 v[4:5], off
	s_waitcnt vmcnt(8)
	s_barrier
	v_and_b32_e32 v4, 15, v12
	v_and_b32_e32 v5, 48, v12
	v_lshlrev_b32_e32 v4, 6, v4
	v_and_b32_e32 v7, 32, v7
	v_or_b32_e32 v6, v4, v5
	v_bitop3_b32 v4, v4, v7, v5 bitop3:0x36
	v_or_b32_e32 v136, s11, v4
	v_lshlrev_b32_e32 v4, 15, v13
	v_and_b32_e32 v4, 0xffff0000, v4
	v_bitop3_b32 v5, v6, s1, v7 bitop3:0xde
	v_lshl_add_u32 v4, v14, 12, v4
	v_and_b32_e32 v6, 1, v13
	v_lshl_or_b32 v4, v6, 6, v4
	v_lshl_add_u32 v132, v15, 1, v4
	v_lshlrev_b32_e32 v4, 15, v16
	v_and_b32_e32 v4, 0xffff0000, v4
	s_waitcnt vmcnt(6)
	s_cmpk_lt_u32 s3, 0x100
	v_lshl_add_u32 v4, v17, 12, v4
	v_and_b32_e32 v6, 1, v16
	s_cselect_b64 s[8:9], -1, 0
	v_lshl_or_b32 v4, v6, 6, v4
	s_add_i32 s33, 0, 0x10000
	s_add_i32 s34, 0, 0x14000
	s_sext_i32_i8 s10, s2
	v_mov_b32_e32 v133, v1
	v_lshl_add_u32 v134, v18, 1, v4
	v_mov_b32_e32 v135, v1
	v_add_u32_e32 v137, s33, v136
	v_add_u32_e32 v138, s34, v136
	v_add_u32_e32 v139, 0, v5
	s_barrier
	s_branch .LBB0_1608

; #define PG8_STAGE(bufoff, gbase, voff) do { _Pragma("unroll") for (int _i = 0; _i < 2; ++_i) \
;         __builtin_amdgcn_global_load_lds((const unsigned*)((const char*)(gbase) + (voff)[_i]), (LAS unsigned*)(lds + (bufoff) + ldsw + _i * 8192), 16, 0, 0); } while (0)
; #define PG8_WAIT_V(n) asm volatile("s_waitcnt vmcnt(" #n ")" ::: "memory")
; #define PG8_BAR __builtin_amdgcn_s_barrier()
;     __device__ __forceinline__ void tile(const f32x4 (&acc)[2][2][4][2], const Unit& u, int wr, int wc, int fr, int fq) const {
;     ...
;             const int cv = 128 * u.pn + 32 * wc + 16 * n + 4 * fq, cg = FF + cv;
; template <class Epi, class Sched, bool DEFER>
; __device__ __forceinline__ void gemm_fast_core(LAS unsigned char* lds, const GemmP g, const Sched& S, const Epi& E, f32x4 (&acc)[2][2][4][2], Unit& cur) {
;     ...
;     PG8_STAGE(PG8_SB(0, 0), cB, voffB); PG8_STAGE(PG8_SB(0, 1), cB + hstepB, voffB); PG8_STAGE(PG8_SA(0, 0), cA, voffA); PG8_STAGE(PG8_SA(0, 1), cA + hstepA, voffA);
;     if (wr == 1) PG8_BAR;
;     PG8_WAIT_V(2); PG8_BAR;
;     PG8_STAGE(PG8_SB(1, 0), cB + kstep, voffB); PG8_STAGE(PG8_SA(1, 0), cA + kstep, voffA); PG8_STAGE(PG8_SB(1, 1), cB + hstepB + kstep, voffB);
;     PG8_WAIT_V(6); PG8_BAR;
.LBB0_1793:
	s_lshl_b32 s7, s7, 5
	s_mov_b64 s[8:9], 0x80
	s_and_b32 s16, s7, 0x60
	s_add_i32 m0, s27, 0x18000
	v_lshl_add_u64 v[6:7], v[6:7], 0, s[8:9]
	s_lshl_b32 s12, s6, 13
	s_lshl_b32 s7, s16, 7
	global_load_lds_dwordx4 v[6:7], off
	v_lshl_add_u64 v[4:5], v[4:5], 0, s[8:9]
	s_add_i32 m0, s27, 0x1a000
	s_add_i32 s42, s27, 0x8000
	s_add_i32 s43, s27, 0xa000
	global_load_lds_dwordx4 v[4:5], off
	v_lshl_add_u64 v[0:1], v[0:1], 0, s[8:9]
	s_mov_b32 m0, s42
	s_add_u32 s10, s30, 0x80080
	global_load_lds_dwordx4 v[0:1], off
	v_lshl_add_u64 v[0:1], v[2:3], 0, s[8:9]
	s_mov_b32 m0, s43
	s_addc_u32 s11, s31, 0
	global_load_lds_dwordx4 v[0:1], off
	s_add_i32 m0, s27, 0x1c000
	v_lshl_add_u64 v[0:1], s[10:11], 0, v[162:163]
	global_load_lds_dwordx4 v[0:1], off
	v_lshl_add_u64 v[0:1], s[10:11], 0, v[160:161]
	s_add_i32 m0, s27, 0x1e000
	v_lshlrev_b32_e32 v3, 2, v11
	global_load_lds_dwordx4 v[0:1], off
	s_waitcnt vmcnt(8)
	s_barrier
	v_bfe_u32 v1, v11, 4, 2
	v_and_b32_e32 v0, 15, v11
	v_lshlrev_b32_e32 v2, 4, v1
	v_lshl_or_b32 v2, v0, 6, v2
	v_and_b32_e32 v3, 32, v3
	s_sext_i32_i16 s33, s4
	v_lshl_or_b32 v195, s6, 6, v0
	v_bitop3_b32 v196, v2, s7, v3 bitop3:0xde
	s_cmpk_lt_u32 s5, 0x100
	v_cmp_eq_u32_e64 s[4:5], 15, v0
	v_cmp_eq_u32_e64 s[6:7], 0, v0
	v_lshlrev_b32_e32 v0, 15, v12
	v_and_b32_e32 v0, 0xffff0000, v0
	v_lshl_or_b32 v204, v1, 2, s16
	v_lshl_add_u32 v0, v13, 12, v0
	v_and_b32_e32 v1, 1, v12
	v_lshl_or_b32 v0, v1, 6, v0
	v_bitop3_b32 v4, v2, s12, v3 bitop3:0xde
	s_cselect_b64 s[10:11], -1, 0
	s_add_u32 s12, s56, 0xb000
	v_lshl_add_u32 v164, v14, 1, v0
	v_lshlrev_b32_e32 v0, 15, v8
	s_addc_u32 s13, s57, 0
	v_and_b32_e32 v0, 0xffff0000, v0
	s_waitcnt vmcnt(6)
	s_add_u32 s14, s56, 0x16000
	v_lshl_add_u32 v0, v9, 12, v0
	v_and_b32_e32 v1, 1, v8
	s_addc_u32 s15, s57, 0
	v_lshl_or_b32 v0, v1, 6, v0
	s_add_i32 s44, 0, 0x10000
	s_add_i32 s45, 0, 0x14000
	v_or_b32_e32 v197, 16, v195
	v_or_b32_e32 v198, 32, v195
	v_or_b32_e32 v199, 48, v195
	v_add_u32_e32 v200, 0x80, v195
	v_add_u32_e32 v201, 0x90, v195
	v_add_u32_e32 v202, 0xa0, v195
	v_add_u32_e32 v203, 0xb0, v195
	v_mov_b32_e32 v165, v163
	v_lshl_add_u32 v166, v10, 1, v0
	v_mov_b32_e32 v167, v163
	v_add_u32_e32 v164, v164, v188
	v_add_u32_e32 v166, v166, v188
	v_add_u32_e32 v205, s44, v196
	v_add_u32_e32 v206, s45, v196
	v_add_u32_e32 v207, 0, v4
	s_movk_i32 s46, 0x2c00
	s_barrier
	s_mov_b32 s98, 0
	s_branch .LBB0_1796

; #define PG8_STAGE(bufoff, gbase, voff) do { _Pragma("unroll") for (int _i = 0; _i < 2; ++_i) \
;         __builtin_amdgcn_global_load_lds((const unsigned*)((const char*)(gbase) + (voff)[_i]), (LAS unsigned*)(lds + (bufoff) + ldsw + _i * 8192), 16, 0, 0); } while (0)
; #define PG8_WAIT_V(n) asm volatile("s_waitcnt vmcnt(" #n ")" ::: "memory")
; #define PG8_BAR __builtin_amdgcn_s_barrier()
; template <class Epi, class Sched, bool DEFER>
; __device__ __forceinline__ void gemm_fast_core(LAS unsigned char* lds, const GemmP g, const Sched& S, const Epi& E, f32x4 (&acc)[2][2][4][2], Unit& cur) {
;     ...
;     PG8_STAGE(PG8_SB(0, 0), cB, voffB); PG8_STAGE(PG8_SB(0, 1), cB + hstepB, voffB); PG8_STAGE(PG8_SA(0, 0), cA, voffA); PG8_STAGE(PG8_SA(0, 1), cA + hstepA, voffA);
;     if (wr == 1) PG8_BAR;
;     PG8_WAIT_V(2); PG8_BAR;
;     PG8_STAGE(PG8_SB(1, 0), cB + kstep, voffB); PG8_STAGE(PG8_SA(1, 0), cA + kstep, voffA); PG8_STAGE(PG8_SB(1, 1), cB + hstepB + kstep, voffB);
;     PG8_WAIT_V(6); PG8_BAR;
.LBB0_1872:
	s_lshl_b32 s15, s10, 13
	s_mov_b64 s[10:11], 0x80
	s_lshl_b32 s3, s3, 12
	s_add_i32 m0, s27, 0x18000
	v_lshl_add_u64 v[6:7], v[6:7], 0, s[10:11]
	s_and_b32 s3, s3, 0x3000
	global_load_lds_dwordx4 v[6:7], off
	v_lshl_add_u64 v[4:5], v[4:5], 0, s[10:11]
	s_add_i32 m0, s27, 0x1a000
	s_add_i32 s34, s27, 0x8000
	s_add_i32 s35, s27, 0xa000
	global_load_lds_dwordx4 v[4:5], off
	v_lshl_add_u64 v[0:1], v[0:1], 0, s[10:11]
	s_mov_b32 m0, s34
	s_add_u32 s12, s20, 0x160080
	global_load_lds_dwordx4 v[0:1], off
	v_lshl_add_u64 v[0:1], v[2:3], 0, s[10:11]
	s_mov_b32 m0, s35
	s_addc_u32 s13, s21, 0
	global_load_lds_dwordx4 v[0:1], off
	s_add_i32 m0, s27, 0x1c000
	v_lshl_add_u64 v[0:1], s[12:13], 0, v[64:65]
	global_load_lds_dwordx4 v[0:1], off
	v_lshl_add_u64 v[0:1], s[12:13], 0, v[66:67]
	s_add_i32 m0, s27, 0x1e000
	v_lshlrev_b32_e32 v3, 2, v8
	global_load_lds_dwordx4 v[0:1], off
	s_waitcnt vmcnt(8)
	s_barrier
	v_and_b32_e32 v0, 15, v8
	v_and_b32_e32 v1, 48, v8
	v_lshlrev_b32_e32 v0, 6, v0
	v_and_b32_e32 v3, 32, v3
	v_or_b32_e32 v2, v0, v1
	v_bitop3_b32 v0, v0, v3, v1 bitop3:0x36
	v_bitop3_b32 v2, v2, s15, v3 bitop3:0xde
	v_or_b32_e32 v3, s3, v0
	v_lshrrev_b32_e32 v1, 1, v9
	v_mul_lo_u32 v0, v10, s2
	s_sext_i32_i8 s44, s7
	s_cmpk_lt_u32 s6, 0x100
	v_mad_u64_u32 v[0:1], s[6:7], v1, s14, v[0:1]
	v_or_b32_e32 v0, v0, v11
	s_mov_b64 s[16:17], 0x160080
	v_add_lshl_u32 v0, v0, v12, 1
	v_mov_b32_e32 v1, v65
	v_lshl_add_u64 v[132:133], v[0:1], 0, s[16:17]
	v_lshrrev_b32_e32 v1, 1, v13
	v_mul_lo_u32 v0, v14, s2
	v_mad_u64_u32 v[0:1], s[2:3], v1, s14, v[0:1]
	s_waitcnt vmcnt(6)
	s_cselect_b64 s[12:13], -1, 0
	v_or_b32_e32 v0, v0, v15
	s_add_i32 s38, 0, 0x10000
	s_add_i32 s40, 0, 0x14000
	v_add_lshl_u32 v0, v0, v16, 1
	v_mov_b32_e32 v1, v65
	v_add_u32_e32 v136, s38, v3
	v_add_u32_e32 v137, s40, v3
	s_add_i32 s38, s38, s26
	s_add_i32 s40, s40, s26
	s_add_i32 s43, 0, 0x18000
	s_add_i32 s42, 0, 0x1c000
	v_lshl_add_u64 v[134:135], v[0:1], 0, s[16:17]
	v_add_u32_e32 v138, 0, v2
	s_add_i32 s36, s27, 0xc000
	s_add_i32 s37, s27, 0xe000
	s_add_i32 s39, s38, 0x2000
	s_add_i32 s41, s40, 0x2000
	v_add_u32_e32 v139, s43, v3
	v_add_u32_e32 v140, s42, v3
	s_add_i32 s43, s43, s26
	s_barrier
	s_branch .LBB0_1875
